# v4 GEMM loop + diff-attn QK read batching, alpha==1 rescale skip, packed->scalar f32; cross-attn: all 12 loads issued up front, QK LDS reads software-pipelined
# speedup vs baseline: 1.0077x; 1.0077x over previous
.LBB0_66:
	v_lshl_add_u64 v[222:223], v[166:167], 0, s[16:17]
	v_mov_b32_e32 v213, v0
	v_mov_b32_e32 v0, v243
	s_add_u32 s14, s1, s16
	s_addc_u32 s15, s24, s17
	global_load_dwordx4 v[66:69], v[222:223], off offset:-16
	global_load_dwordx4 v[70:73], v[222:223], off offset:-32
	global_load_dwordx4 v[74:77], v[222:223], off offset:-48
	global_load_dwordx4 v[78:81], v[222:223], off offset:-64
	global_load_dwordx4 v[82:85], v[222:223], off offset:48
	global_load_dwordx4 v[86:89], v[222:223], off offset:32
	global_load_dwordx4 v[90:93], v[222:223], off offset:16
	global_load_dwordx4 v[94:97], v[222:223], off
	v_ashrrev_i32_e32 v214, 3, v0
	v_ashrrev_i32_e32 v215, 31, v214
	v_lshlrev_b64 v[214:215], 9, v[214:215]
	v_and_b32_e32 v0, 7, v0
	v_lshl_or_b32 v214, v0, 4, v214
	v_lshl_add_u64 v[238:239], s[14:15], 0, v[214:215]
	s_mov_b32 s0, 0x5080000
	v_add_co_u32_e32 v214, vcc, s0, v238
	s_mov_b32 s0, 0x5084000
	s_nop 0
	v_addc_co_u32_e32 v215, vcc, 0, v239, vcc
	v_add_co_u32_e32 v218, vcc, s0, v238
	s_mov_b32 s0, 0x5088000
	s_nop 0
	v_addc_co_u32_e32 v219, vcc, 0, v239, vcc
	v_add_co_u32_e32 v234, vcc, s0, v238
	s_mov_b32 s0, 0x508c000
	s_nop 0
	v_addc_co_u32_e32 v235, vcc, 0, v239, vcc
	global_load_dwordx4 v[214:217], v[214:215], off
	v_add_co_u32_e32 v238, vcc, s0, v238
	global_load_dwordx4 v[218:221], v[218:219], off
	s_nop 0
	v_addc_co_u32_e32 v239, vcc, 0, v239, vcc
	global_load_dwordx4 v[234:237], v[234:235], off
	v_mov_b32_e32 v0, v243
	global_load_dwordx4 v[238:241], v[238:239], off
	s_add_i32 s25, s25, -1
	s_add_u32 s1, s1, 0x80
	s_addc_u32 s24, s24, 0
	s_cmp_eq_u32 s25, 0
	s_mov_b64 s[14:15], 0x20000
	v_lshl_add_u64 v[166:167], v[166:167], 0, s[14:15]
	s_barrier
	s_waitcnt vmcnt(8)
	ds_write_b128 v178, v[78:81]
	ds_write_b128 v179, v[74:77]
	ds_write_b128 v180, v[70:73]
	ds_write_b128 v181, v[66:69]
	s_waitcnt vmcnt(4)
	ds_write_b128 v182, v[94:97]
	ds_write_b128 v183, v[90:93]
	ds_write_b128 v184, v[86:89]
	ds_write_b128 v185, v[82:85]
	v_lshlrev_b32_e32 v82, 4, v0
	v_and_b32_e32 v83, 0xffffff80, v82
	v_bitop3_b32 v82, v82, s82, v0 bitop3:0x48
	v_and_b32_e32 v0, 0x80, v0
	v_cmp_eq_u32_e32 vcc, 0, v0
	v_add3_u32 v0, s78, v82, v83
	s_waitcnt vmcnt(3)
	v_cndmask_b32_e32 v69, v215, v217, vcc
	v_cndmask_b32_e32 v68, v214, v216, vcc
	v_cndmask_b32_e32 v67, v217, v215, vcc
	v_cndmask_b32_e32 v66, v216, v214, vcc
	ds_write_b128 v0, v[66:69] offset:32768
	s_waitcnt vmcnt(2)
	v_cndmask_b32_e32 v73, v219, v221, vcc
	v_cndmask_b32_e32 v72, v218, v220, vcc
	v_cndmask_b32_e32 v71, v221, v219, vcc
	v_cndmask_b32_e32 v70, v220, v218, vcc
	ds_write_b128 v0, v[70:73] offset:36864
	s_waitcnt vmcnt(1)
	v_cndmask_b32_e32 v77, v235, v237, vcc
	v_cndmask_b32_e32 v76, v234, v236, vcc
	v_cndmask_b32_e32 v75, v237, v235, vcc
	v_cndmask_b32_e32 v74, v236, v234, vcc
	ds_write_b128 v0, v[74:77] offset:40960
	s_waitcnt vmcnt(0)
	v_cndmask_b32_e32 v81, v239, v241, vcc
	v_cndmask_b32_e32 v80, v238, v240, vcc
	v_cndmask_b32_e32 v79, v241, v239, vcc
	v_cndmask_b32_e32 v78, v240, v238, vcc
	ds_write_b128 v0, v[78:81] offset:45056
	v_add_u32_e32 v211, v169, v170
	v_add_u32_e32 v218, v169, v171
	v_add_u32_e32 v219, v169, v172
	v_add_u32_e32 v220, v169, v173
	v_add_u32_e32 v221, v169, v174
	v_add_u32_e32 v222, v169, v175
	v_add_u32_e32 v223, v169, v176
	v_add_u32_e32 v0, v169, v168
	s_waitcnt lgkmcnt(0)
	s_barrier
	ds_read_b128 v[214:217], v0
	ds_read_b128 v[234:237], v211
	ds_read_b128 v[238:241], v218
	ds_read_b128 v[246:249], v219
	s_waitcnt lgkmcnt(3)
	v_mfma_f32_32x32x16_bf16 v[66:81], v[214:217], v[98:101], 0
	ds_read_b128 v[214:217], v220
	s_waitcnt lgkmcnt(3)
	v_mfma_f32_32x32x16_bf16 v[66:81], v[234:237], v[102:105], v[66:81]
	ds_read_b128 v[234:237], v221
	s_waitcnt lgkmcnt(3)
	v_mfma_f32_32x32x16_bf16 v[66:81], v[238:241], v[106:109], v[66:81]
	ds_read_b128 v[238:241], v222
	s_waitcnt lgkmcnt(3)
	v_mfma_f32_32x32x16_bf16 v[66:81], v[246:249], v[110:113], v[66:81]
	ds_read_b128 v[246:249], v223
	s_waitcnt lgkmcnt(3)
	v_mfma_f32_32x32x16_bf16 v[66:81], v[214:217], v[114:117], v[66:81]
	ds_read_b128 v[214:217], v0 offset:256
	s_waitcnt lgkmcnt(3)
	v_mfma_f32_32x32x16_bf16 v[66:81], v[234:237], v[118:121], v[66:81]
	ds_read_b128 v[234:237], v211 offset:256
	s_waitcnt lgkmcnt(3)
	v_mfma_f32_32x32x16_bf16 v[66:81], v[238:241], v[122:125], v[66:81]
	ds_read_b128 v[238:241], v218 offset:256
	s_waitcnt lgkmcnt(3)
	v_mfma_f32_32x32x16_bf16 v[66:81], v[246:249], v[126:129], v[66:81]
	ds_read_b128 v[246:249], v219 offset:256
	s_waitcnt lgkmcnt(3)
	v_mfma_f32_32x32x16_bf16 v[66:81], v[214:217], v[130:133], v[66:81]
	ds_read_b128 v[214:217], v220 offset:256
	s_waitcnt lgkmcnt(3)
	v_mfma_f32_32x32x16_bf16 v[66:81], v[234:237], v[134:137], v[66:81]
	ds_read_b128 v[234:237], v221 offset:256
	s_waitcnt lgkmcnt(3)
	v_mfma_f32_32x32x16_bf16 v[66:81], v[238:241], v[138:141], v[66:81]
	ds_read_b128 v[238:241], v222 offset:256
	s_waitcnt lgkmcnt(3)
	v_mfma_f32_32x32x16_bf16 v[66:81], v[246:249], v[142:145], v[66:81]
	ds_read_b128 v[246:249], v223 offset:256
	s_waitcnt lgkmcnt(3)
	v_mfma_f32_32x32x16_bf16 v[66:81], v[214:217], v[146:149], v[66:81]
	ds_read_b128 v[214:217], v0 offset:16384
	s_waitcnt lgkmcnt(3)
	v_mfma_f32_32x32x16_bf16 v[66:81], v[234:237], v[150:153], v[66:81]
	ds_read_b128 v[234:237], v211 offset:16384
	s_waitcnt lgkmcnt(3)
	v_mfma_f32_32x32x16_bf16 v[66:81], v[238:241], v[154:157], v[66:81]
	ds_read_b128 v[238:241], v218 offset:16384
	s_waitcnt lgkmcnt(3)
	v_mfma_f32_32x32x16_bf16 v[66:81], v[246:249], v[158:161], v[66:81]
	ds_read_b128 v[246:249], v219 offset:16384
	s_waitcnt lgkmcnt(3)
	v_mfma_f32_32x32x16_bf16 v[82:97], v[214:217], v[98:101], 0
	ds_read_b128 v[214:217], v220 offset:16384
	s_waitcnt lgkmcnt(3)
	v_mfma_f32_32x32x16_bf16 v[82:97], v[234:237], v[102:105], v[82:97]
	ds_read_b128 v[234:237], v221 offset:16384
	s_waitcnt lgkmcnt(3)
	v_mfma_f32_32x32x16_bf16 v[82:97], v[238:241], v[106:109], v[82:97]
	ds_read_b128 v[238:241], v222 offset:16384
	s_waitcnt lgkmcnt(3)
	v_mfma_f32_32x32x16_bf16 v[82:97], v[246:249], v[110:113], v[82:97]
	ds_read_b128 v[246:249], v223 offset:16384
	s_waitcnt lgkmcnt(3)
	v_mfma_f32_32x32x16_bf16 v[82:97], v[214:217], v[114:117], v[82:97]
	ds_read_b128 v[214:217], v0 offset:16640
	s_waitcnt lgkmcnt(3)
	v_mfma_f32_32x32x16_bf16 v[82:97], v[234:237], v[118:121], v[82:97]
	ds_read_b128 v[234:237], v211 offset:16640
	s_waitcnt lgkmcnt(3)
	v_mfma_f32_32x32x16_bf16 v[82:97], v[238:241], v[122:125], v[82:97]
	ds_read_b128 v[238:241], v218 offset:16640
	s_waitcnt lgkmcnt(3)
	v_mfma_f32_32x32x16_bf16 v[82:97], v[246:249], v[126:129], v[82:97]
	ds_read_b128 v[246:249], v219 offset:16640
	s_waitcnt lgkmcnt(3)
	v_mfma_f32_32x32x16_bf16 v[82:97], v[214:217], v[130:133], v[82:97]
	ds_read_b128 v[214:217], v220 offset:16640
	s_waitcnt lgkmcnt(3)
	v_mfma_f32_32x32x16_bf16 v[82:97], v[234:237], v[134:137], v[82:97]
	ds_read_b128 v[234:237], v221 offset:16640
	s_waitcnt lgkmcnt(3)
	v_mfma_f32_32x32x16_bf16 v[82:97], v[238:241], v[138:141], v[82:97]
	ds_read_b128 v[238:241], v222 offset:16640
	s_waitcnt lgkmcnt(3)
	v_mfma_f32_32x32x16_bf16 v[82:97], v[246:249], v[142:145], v[82:97]
	ds_read_b128 v[246:249], v223 offset:16640
	s_waitcnt lgkmcnt(3)
	v_mfma_f32_32x32x16_bf16 v[82:97], v[214:217], v[146:149], v[82:97]
	s_waitcnt lgkmcnt(2)
	v_mfma_f32_32x32x16_bf16 v[82:97], v[234:237], v[150:153], v[82:97]
	s_waitcnt lgkmcnt(1)
	v_mfma_f32_32x32x16_bf16 v[82:97], v[238:241], v[154:157], v[82:97]
	s_waitcnt lgkmcnt(0)
	v_mfma_f32_32x32x16_bf16 v[82:97], v[246:249], v[158:161], v[82:97]
	v_mov_b32_e32 v234, 0x8010
	v_mov_b32_e32 v236, 0x8014
	v_mov_b32_e32 v238, 0x8018
	v_mov_b32_e32 v240, 0x801c
	v_max_f32_e32 v0, v68, v68
	v_max_f32_e32 v0, 0xf149f2ca, v0
	v_max3_f32 v0, v0, v72, v76
	v_max3_f32 v211, v66, s83, v70
	v_max3_f32 v211, v211, v74, v78
	v_max3_f32 v215, v69, s83, v73
	v_max3_f32 v214, v67, s83, v71
	v_max3_f32 v215, v215, v77, v81
	v_max3_f32 v214, v214, v75, v79
	s_nop 7
	v_max3_f32 v0, v0, v80, v84
	v_max3_f32 v215, v215, v85, v89
	v_max3_f32 v211, v211, v82, v86
	v_max3_f32 v214, v214, v83, v87
	v_max3_f32 v0, v0, v88, v92
	v_max3_f32 v215, v215, v93, v97
	v_max3_f32 v211, v211, v90, v94
	v_max3_f32 v214, v214, v91, v95
	v_max3_f32 v0, v0, v96, v215
	v_max3_f32 v0, v211, v214, v0
	ds_bpermute_b32 v211, v194, v0
	s_waitcnt lgkmcnt(0)
	v_max3_f32 v211, v212, v0, v211
	v_sub_f32_e32 v66, v66, v211
	v_exp_f32_e32 v214, v66
	v_sub_f32_e32 v66, v67, v211
	v_exp_f32_e32 v216, v66
	v_sub_f32_e32 v66, v68, v211
	v_exp_f32_e32 v215, v66
	v_sub_f32_e32 v66, v69, v211
	v_exp_f32_e32 v217, v66
	v_sub_f32_e32 v66, v70, v211
	v_sub_f32_e32 v70, v78, v211
	v_exp_f32_e32 v222, v70
	v_sub_f32_e32 v70, v79, v211
	v_exp_f32_e32 v224, v70
	v_sub_f32_e32 v70, v80, v211
	v_exp_f32_e32 v223, v70
	v_sub_f32_e32 v70, v81, v211
	v_exp_f32_e32 v225, v70
	v_sub_f32_e32 v70, v82, v211
	v_exp_f32_e32 v246, v70
	v_sub_f32_e32 v70, v83, v211
	v_exp_f32_e32 v248, v70
	v_sub_f32_e32 v70, v84, v211
	v_exp_f32_e32 v247, v70
	v_sub_f32_e32 v70, v85, v211
	v_exp_f32_e32 v249, v70
	v_sub_f32_e32 v70, v86, v211
	v_exp_f32_e32 v86, v70
	v_sub_f32_e32 v70, v87, v211
	v_exp_f32_e32 v250, v70
	v_sub_f32_e32 v70, v88, v211
	v_exp_f32_e32 v87, v70
	v_sub_f32_e32 v70, v89, v211
	v_exp_f32_e32 v251, v70
	v_sub_f32_e32 v70, v90, v211
	v_exp_f32_e32 v88, v70
	v_sub_f32_e32 v70, v91, v211
	v_exp_f32_e32 v218, v66
	v_sub_f32_e32 v66, v71, v211
	v_exp_f32_e32 v90, v70
	v_sub_f32_e32 v70, v92, v211
	v_exp_f32_e32 v220, v66
	v_sub_f32_e32 v66, v72, v211
	v_exp_f32_e32 v89, v70
	v_sub_f32_e32 v70, v93, v211
	v_exp_f32_e32 v219, v66
	v_sub_f32_e32 v66, v73, v211
	v_sub_f32_e32 v67, v75, v211
	v_exp_f32_e32 v91, v70
	v_sub_f32_e32 v70, v94, v211
	v_exp_f32_e32 v221, v66
	v_sub_f32_e32 v66, v74, v211
	v_exp_f32_e32 v68, v67
	v_sub_f32_e32 v67, v76, v211
	v_sub_f32_e32 v69, v77, v211
	v_exp_f32_e32 v92, v70
	v_sub_f32_e32 v70, v95, v211
	v_exp_f32_e32 v66, v66
	v_exp_f32_e32 v67, v67
	v_exp_f32_e32 v69, v69
	v_exp_f32_e32 v94, v70
	v_sub_f32_e32 v70, v96, v211
	v_exp_f32_e32 v93, v70
	v_sub_f32_e32 v70, v97, v211
	v_exp_f32_e32 v95, v70
	v_pk_add_f32 v[70:71], v[214:215], 0 op_sel_hi:[1,0]
	v_pk_add_f32 v[72:73], v[216:217], 0 op_sel_hi:[1,0]
	ds_read2st64_b64 v[74:77], v186 offset0:64 offset1:80
	ds_read2st64_b64 v[78:81], v187 offset0:64 offset1:80
	v_pk_add_f32 v[70:71], v[218:219], v[70:71]
	v_pk_add_f32 v[72:73], v[220:221], v[72:73]
	v_pk_add_f32 v[70:71], v[66:67], v[70:71]
	v_pk_add_f32 v[72:73], v[68:69], v[72:73]
	v_pk_add_f32 v[70:71], v[222:223], v[70:71]
	v_pk_add_f32 v[72:73], v[224:225], v[72:73]
	v_sub_f32_e32 v0, v212, v211
	v_pk_add_f32 v[70:71], v[246:247], v[70:71]
	v_pk_add_f32 v[72:73], v[248:249], v[72:73]
	v_exp_f32_e32 v96, v0
	v_pk_add_f32 v[70:71], v[86:87], v[70:71]
	v_pk_add_f32 v[72:73], v[250:251], v[72:73]
	s_waitcnt lgkmcnt(1)
	v_mov_b32_e32 v82, v74
	v_mov_b32_e32 v83, v75
	s_waitcnt lgkmcnt(0)
	v_mov_b32_e32 v84, v78
	v_mov_b32_e32 v85, v79
	v_pk_add_f32 v[70:71], v[88:89], v[70:71]
	v_pk_add_f32 v[72:73], v[90:91], v[72:73]
	v_pk_add_f32 v[70:71], v[92:93], v[70:71]
	v_pk_add_f32 v[72:73], v[94:95], v[72:73]
	v_pk_mul_f32 v[64:65], v[64:65], v[96:97] op_sel_hi:[1,0]
	v_pk_add_f32 v[70:71], v[70:71], v[72:73]
	v_pk_mul_f32 v[62:63], v[62:63], v[96:97] op_sel_hi:[1,0]
	v_pk_mul_f32 v[60:61], v[60:61], v[96:97] op_sel_hi:[1,0]
	v_pk_mul_f32 v[58:59], v[58:59], v[96:97] op_sel_hi:[1,0]
	v_pk_mul_f32 v[56:57], v[56:57], v[96:97] op_sel_hi:[1,0]
	v_pk_mul_f32 v[54:55], v[54:55], v[96:97] op_sel_hi:[1,0]
	v_pk_mul_f32 v[52:53], v[52:53], v[96:97] op_sel_hi:[1,0]
	v_pk_mul_f32 v[50:51], v[50:51], v[96:97] op_sel_hi:[1,0]
	v_add_f32_e32 v0, v70, v71
	v_cvt_pk_bf16_f32 v70, v214, v216
	v_cvt_pk_bf16_f32 v71, v215, v217
	v_cvt_pk_bf16_f32 v72, v218, v220
	v_cvt_pk_bf16_f32 v73, v219, v221
	v_mov_b32_e32 v78, v76
	v_mov_b32_e32 v79, v77
	v_mfma_f32_32x32x16_bf16 v[50:65], v[82:85], v[70:73], v[50:65]
	ds_read_b64 v[82:83], v188 offset:32768
	ds_read_b64 v[84:85], v189 offset:32768
	ds_read_b64 v[74:75], v190 offset:32768
	ds_read_b64 v[76:77], v191 offset:32768
	v_mul_f32_e64 v48, v48, v96
	v_mul_f32_e64 v49, v49, v96
	v_pk_mul_f32 v[46:47], v[46:47], v[96:97] op_sel_hi:[1,0]
	v_pk_mul_f32 v[44:45], v[44:45], v[96:97] op_sel_hi:[1,0]
	v_pk_mul_f32 v[42:43], v[42:43], v[96:97] op_sel_hi:[1,0]
	v_pk_mul_f32 v[40:41], v[40:41], v[96:97] op_sel_hi:[1,0]
	v_pk_mul_f32 v[38:39], v[38:39], v[96:97] op_sel_hi:[1,0]
	v_pk_mul_f32 v[36:37], v[36:37], v[96:97] op_sel_hi:[1,0]
	v_pk_mul_f32 v[34:35], v[34:35], v[96:97] op_sel_hi:[1,0]
	v_pk_mul_f32 v[32:33], v[32:33], v[96:97] op_sel_hi:[1,0]
	v_pk_mul_f32 v[30:31], v[30:31], v[96:97] op_sel_hi:[1,0]
	v_pk_mul_f32 v[28:29], v[28:29], v[96:97] op_sel_hi:[1,0]
	v_pk_mul_f32 v[26:27], v[26:27], v[96:97] op_sel_hi:[1,0]
	v_pk_mul_f32 v[24:25], v[24:25], v[96:97] op_sel_hi:[1,0]
	v_pk_mul_f32 v[22:23], v[22:23], v[96:97] op_sel_hi:[1,0]
	v_pk_mul_f32 v[20:21], v[20:21], v[96:97] op_sel_hi:[1,0]
	v_pk_mul_f32 v[18:19], v[18:19], v[96:97] op_sel_hi:[1,0]
	v_pk_mul_f32 v[16:17], v[16:17], v[96:97] op_sel_hi:[1,0]
	v_pk_mul_f32 v[14:15], v[14:15], v[96:97] op_sel_hi:[1,0]
	v_pk_mul_f32 v[12:13], v[12:13], v[96:97] op_sel_hi:[1,0]
	v_pk_mul_f32 v[10:11], v[10:11], v[96:97] op_sel_hi:[1,0]
	v_pk_mul_f32 v[8:9], v[8:9], v[96:97] op_sel_hi:[1,0]
	v_pk_mul_f32 v[6:7], v[6:7], v[96:97] op_sel_hi:[1,0]
	v_pk_mul_f32 v[4:5], v[4:5], v[96:97] op_sel_hi:[1,0]
	v_pk_mul_f32 v[2:3], v[2:3], v[96:97] op_sel_hi:[1,0]
	s_waitcnt lgkmcnt(2)
	v_mfma_f32_32x32x16_bf16 v[34:49], v[82:85], v[70:73], v[34:49]
	v_cvt_pk_bf16_f32 v66, v66, v68
	v_cvt_pk_bf16_f32 v67, v67, v69
	v_cvt_pk_bf16_f32 v68, v222, v224
	v_cvt_pk_bf16_f32 v69, v223, v225
	v_fmac_f32_e32 v0, v213, v96
	v_mov_b32_e32 v212, v211
	v_mfma_f32_32x32x16_bf16 v[18:33], v[78:81], v[70:73], v[18:33]
	s_waitcnt lgkmcnt(0)
	v_mfma_f32_32x32x16_bf16 v[2:17], v[74:77], v[70:73], v[2:17]
	ds_read2st64_b64 v[70:73], v192 offset0:64 offset1:80
	ds_read2st64_b64 v[74:77], v193 offset0:64 offset1:80
	s_waitcnt lgkmcnt(1)
	v_mov_b32_e32 v78, v70
	v_mov_b32_e32 v79, v71
	s_waitcnt lgkmcnt(0)
	v_mov_b32_e32 v80, v74
	v_mov_b32_e32 v81, v75
	v_mov_b32_e32 v74, v72
	v_mov_b32_e32 v75, v73
	v_mfma_f32_32x32x16_bf16 v[50:65], v[78:81], v[66:69], v[50:65]
	ds_read_b64 v[78:79], v195 offset:32768
	ds_read_b64 v[80:81], v196 offset:32768
	ds_read_b64 v[70:71], v197 offset:32768
	ds_read_b64 v[72:73], v198 offset:32768
	s_waitcnt lgkmcnt(2)
	v_mfma_f32_32x32x16_bf16 v[34:49], v[78:81], v[66:69], v[34:49]
	v_mfma_f32_32x32x16_bf16 v[18:33], v[74:77], v[66:69], v[18:33]
	ds_read2st64_b64 v[74:77], v199 offset0:64 offset1:80
	ds_read2st64_b64 v[78:81], v200 offset0:64 offset1:80
	s_waitcnt lgkmcnt(1)
	v_mov_b32_e32 v82, v74
	v_mov_b32_e32 v83, v75
	s_waitcnt lgkmcnt(0)
	v_mov_b32_e32 v84, v78
	v_mov_b32_e32 v85, v79
	v_mfma_f32_32x32x16_bf16 v[2:17], v[70:73], v[66:69], v[2:17]
	v_cvt_pk_bf16_f32 v70, v246, v248
	v_cvt_pk_bf16_f32 v71, v247, v249
	v_cvt_pk_bf16_f32 v72, v86, v250
	v_cvt_pk_bf16_f32 v73, v87, v251
	v_mov_b32_e32 v78, v76
	v_mov_b32_e32 v79, v77
	v_cvt_pk_bf16_f32 v66, v88, v90
	v_mfma_f32_32x32x16_bf16 v[50:65], v[82:85], v[70:73], v[50:65]
	ds_read_b64 v[82:83], v201 offset:32768
	ds_read_b64 v[84:85], v202 offset:32768
	ds_read_b64 v[74:75], v203 offset:32768
	ds_read_b64 v[76:77], v204 offset:32768
	v_cvt_pk_bf16_f32 v67, v89, v91
	v_cvt_pk_bf16_f32 v68, v92, v94
	v_cvt_pk_bf16_f32 v69, v93, v95
	s_waitcnt lgkmcnt(2)
	v_mfma_f32_32x32x16_bf16 v[34:49], v[82:85], v[70:73], v[34:49]
	v_mfma_f32_32x32x16_bf16 v[18:33], v[78:81], v[70:73], v[18:33]
	s_waitcnt lgkmcnt(0)
	v_mfma_f32_32x32x16_bf16 v[2:17], v[74:77], v[70:73], v[2:17]
	ds_read2st64_b64 v[70:73], v205 offset0:64 offset1:80
	ds_read2st64_b64 v[74:77], v206 offset0:64 offset1:80
	s_waitcnt lgkmcnt(1)
	v_mov_b32_e32 v78, v70
	v_mov_b32_e32 v79, v71
	s_waitcnt lgkmcnt(0)
	v_mov_b32_e32 v80, v74
	v_mov_b32_e32 v81, v75
	v_mov_b32_e32 v74, v72
	v_mov_b32_e32 v75, v73
	v_mfma_f32_32x32x16_bf16 v[50:65], v[78:81], v[66:69], v[50:65]
	ds_read_b64 v[78:79], v207 offset:32768
	ds_read_b64 v[80:81], v208 offset:32768
	ds_read_b64 v[70:71], v209 offset:32768
	ds_read_b64 v[72:73], v210 offset:32768
	s_waitcnt lgkmcnt(2)
	v_mfma_f32_32x32x16_bf16 v[34:49], v[78:81], v[66:69], v[34:49]
	v_mfma_f32_32x32x16_bf16 v[18:33], v[74:77], v[66:69], v[18:33]
	s_waitcnt lgkmcnt(0)
	v_mfma_f32_32x32x16_bf16 v[2:17], v[70:73], v[66:69], v[2:17]
	s_cbranch_scc0 .LBB0_66
	ds_bpermute_b32 v66, v194, v0
	s_lshl_b32 s80, s80, 8
	s_mov_b64 s[14:15], 0
	s_waitcnt lgkmcnt(0)
	v_add_f32_e32 v0, v0, v66
	v_div_scale_f32 v66, s[0:1], v0, v0, 1.0
	v_rcp_f32_e32 v67, v66
	s_nop 0
	v_fma_f32 v68, -v66, v67, 1.0
	v_fmac_f32_e32 v67, v68, v67
	v_div_scale_f32 v68, vcc, 1.0, v0, 1.0
	v_mul_f32_e32 v69, v68, v67
	v_fma_f32 v70, -v66, v69, v68
	v_fmac_f32_e32 v69, v70, v67
	v_fma_f32 v66, -v66, v69, v68
	v_div_fmas_f32 v66, v66, v67, v69
	v_div_fixup_f32 v0, v66, v0, 1.0
	v_pk_mul_f32 v[50:51], v[50:51], v[0:1] op_sel_hi:[1,0]
	v_pk_mul_f32 v[52:53], v[52:53], v[0:1] op_sel_hi:[1,0]
	v_pk_mul_f32 v[34:35], v[34:35], v[0:1] op_sel_hi:[1,0]
	v_pk_mul_f32 v[36:37], v[36:37], v[0:1] op_sel_hi:[1,0]
	v_pk_mul_f32 v[18:19], v[18:19], v[0:1] op_sel_hi:[1,0]
	v_pk_mul_f32 v[20:21], v[20:21], v[0:1] op_sel_hi:[1,0]
	v_pk_mul_f32 v[2:3], v[2:3], v[0:1] op_sel_hi:[1,0]
	v_pk_mul_f32 v[4:5], v[4:5], v[0:1] op_sel_hi:[1,0]
	v_lshl_add_u64 v[66:67], v[162:163], 0, s[80:81]
	v_cvt_pk_bf16_f32 v50, v50, v51
	v_cvt_pk_bf16_f32 v51, v52, v53
	v_cvt_pk_bf16_f32 v34, v34, v35
	v_cvt_pk_bf16_f32 v35, v36, v37
	v_cvt_pk_bf16_f32 v18, v18, v19
	v_cvt_pk_bf16_f32 v19, v20, v21
	v_cvt_pk_bf16_f32 v2, v2, v3
	v_cvt_pk_bf16_f32 v3, v4, v5
	global_store_dwordx2 v[66:67], v[50:51], off
	v_pk_mul_f32 v[50:51], v[54:55], v[0:1] op_sel_hi:[1,0]
	v_pk_mul_f32 v[52:53], v[56:57], v[0:1] op_sel_hi:[1,0]
	global_store_dwordx2 v[66:67], v[34:35], off offset:64
	v_pk_mul_f32 v[34:35], v[38:39], v[0:1] op_sel_hi:[1,0]
	v_pk_mul_f32 v[36:37], v[40:41], v[0:1] op_sel_hi:[1,0]
	global_store_dwordx2 v[66:67], v[18:19], off offset:128
	v_pk_mul_f32 v[18:19], v[22:23], v[0:1] op_sel_hi:[1,0]
	v_pk_mul_f32 v[20:21], v[24:25], v[0:1] op_sel_hi:[1,0]
	global_store_dwordx2 v[66:67], v[2:3], off offset:192
	v_pk_mul_f32 v[2:3], v[6:7], v[0:1] op_sel_hi:[1,0]
	v_pk_mul_f32 v[4:5], v[8:9], v[0:1] op_sel_hi:[1,0]
	v_cvt_pk_bf16_f32 v50, v50, v51
	v_cvt_pk_bf16_f32 v51, v52, v53
	v_cvt_pk_bf16_f32 v34, v34, v35
	v_cvt_pk_bf16_f32 v35, v36, v37
	v_cvt_pk_bf16_f32 v18, v18, v19
	v_cvt_pk_bf16_f32 v19, v20, v21
	v_cvt_pk_bf16_f32 v2, v2, v3
	v_cvt_pk_bf16_f32 v3, v4, v5
	global_store_dwordx2 v[66:67], v[50:51], off offset:16
	v_pk_mul_f32 v[50:51], v[58:59], v[0:1] op_sel_hi:[1,0]
	v_pk_mul_f32 v[52:53], v[60:61], v[0:1] op_sel_hi:[1,0]
	global_store_dwordx2 v[66:67], v[34:35], off offset:80
	v_pk_mul_f32 v[34:35], v[42:43], v[0:1] op_sel_hi:[1,0]
	v_pk_mul_f32 v[36:37], v[44:45], v[0:1] op_sel_hi:[1,0]
	global_store_dwordx2 v[66:67], v[18:19], off offset:144
	v_pk_mul_f32 v[18:19], v[26:27], v[0:1] op_sel_hi:[1,0]
	v_pk_mul_f32 v[20:21], v[28:29], v[0:1] op_sel_hi:[1,0]
	global_store_dwordx2 v[66:67], v[2:3], off offset:208
	v_pk_mul_f32 v[2:3], v[10:11], v[0:1] op_sel_hi:[1,0]
	v_pk_mul_f32 v[4:5], v[12:13], v[0:1] op_sel_hi:[1,0]
	v_cvt_pk_bf16_f32 v50, v50, v51
	v_cvt_pk_bf16_f32 v51, v52, v53
	v_cvt_pk_bf16_f32 v34, v34, v35
	v_cvt_pk_bf16_f32 v35, v36, v37
	v_cvt_pk_bf16_f32 v18, v18, v19
	v_cvt_pk_bf16_f32 v19, v20, v21
	v_cvt_pk_bf16_f32 v2, v2, v3
	v_cvt_pk_bf16_f32 v3, v4, v5
	global_store_dwordx2 v[66:67], v[50:51], off offset:32
	v_pk_mul_f32 v[50:51], v[62:63], v[0:1] op_sel_hi:[1,0]
	v_pk_mul_f32 v[52:53], v[64:65], v[0:1] op_sel_hi:[1,0]
	global_store_dwordx2 v[66:67], v[34:35], off offset:96
	v_pk_mul_f32 v[34:35], v[46:47], v[0:1] op_sel_hi:[1,0]
	v_pk_mul_f32 v[36:37], v[48:49], v[0:1] op_sel_hi:[1,0]
	global_store_dwordx2 v[66:67], v[18:19], off offset:160
	v_pk_mul_f32 v[18:19], v[30:31], v[0:1] op_sel_hi:[1,0]
	v_pk_mul_f32 v[20:21], v[32:33], v[0:1] op_sel_hi:[1,0]
	global_store_dwordx2 v[66:67], v[2:3], off offset:224
	v_pk_mul_f32 v[2:3], v[14:15], v[0:1] op_sel_hi:[1,0]
	v_pk_mul_f32 v[4:5], v[16:17], v[0:1] op_sel_hi:[1,0]
	v_cvt_pk_bf16_f32 v50, v50, v51
	v_cvt_pk_bf16_f32 v51, v52, v53
	v_cvt_pk_bf16_f32 v34, v34, v35
	v_cvt_pk_bf16_f32 v35, v36, v37
	v_cvt_pk_bf16_f32 v18, v18, v19
	v_cvt_pk_bf16_f32 v19, v20, v21
	v_cvt_pk_bf16_f32 v2, v2, v3
	v_cvt_pk_bf16_f32 v3, v4, v5
	s_mov_b32 s80, 1
	s_and_b64 vcc, exec, s[22:23]
	global_store_dwordx2 v[66:67], v[50:51], off offset:48
	global_store_dwordx2 v[66:67], v[34:35], off offset:112
	global_store_dwordx2 v[66:67], v[18:19], off offset:176
	global_store_dwordx2 v[66:67], v[2:3], off offset:240
	s_cbranch_vccz .LBB0_65
	s_add_i32 s10, s10, s56
	s_add_i32 s11, s11, s73
	s_cmpk_gt_i32 s10, 0x1ff
	v_xor_b32_e32 v246, 32, v242
	s_cbranch_scc0 .LBB0_64
	v_mov_b32_e32 v248, v227
	v_mov_b32_e32 v249, v229
	v_mov_b32_e32 v250, v231
	v_mov_b32_e32 v251, v233

.LBB0_112:
	s_or_b64 exec, exec, s[14:15]
	s_nop 7
	v_max_f32_e32 v155, v68, v68
	v_max_f32_e32 v155, 0xf149f2ca, v155
	v_max3_f32 v158, v69, s83, v73
	v_max3_f32 v156, v66, s83, v70
	v_max3_f32 v157, v67, s83, v71
	v_max3_f32 v155, v155, v72, v76
	v_max3_f32 v158, v158, v77, v81
	v_max3_f32 v156, v156, v74, v78
	v_max3_f32 v157, v157, v75, v79
	v_max3_f32 v155, v155, v80, v84
	v_max3_f32 v158, v158, v85, v89
	v_max3_f32 v156, v156, v82, v86
	v_max3_f32 v157, v157, v83, v87
	v_max3_f32 v155, v155, v88, v92
	v_max3_f32 v158, v158, v93, v97
	v_max3_f32 v156, v156, v90, v94
	v_max3_f32 v157, v157, v91, v95
	v_max3_f32 v155, v155, v96, v158
	v_max3_f32 v155, v156, v157, v155
	ds_bpermute_b32 v156, v164, v155
	v_add_u32_e32 v0, s28, v180
	v_cvt_f32_i32_e32 v0, v0
	s_waitcnt lgkmcnt(0)
	v_max_f32_e32 v156, v156, v156
	v_max_f32_e32 v155, v155, v156
	v_fmac_f32_e32 v155, v170, v0
	v_max_f32_e32 v156, v154, v154
	v_max_f32_e32 v206, v156, v155
	v_fma_f32 v0, -v170, v0, v206
	v_sub_f32_e32 v66, v66, v0
	v_exp_f32_e32 v156, v66
	v_sub_f32_e32 v66, v67, v0
	v_exp_f32_e32 v158, v66
	v_sub_f32_e32 v66, v68, v0
	v_exp_f32_e32 v157, v66
	v_sub_f32_e32 v66, v69, v0
	v_exp_f32_e32 v159, v66
	v_sub_f32_e32 v66, v70, v0
	v_exp_f32_e32 v160, v66
	v_sub_f32_e32 v66, v71, v0
	v_exp_f32_e32 v162, v66
	v_sub_f32_e32 v66, v72, v0
	v_sub_f32_e32 v72, v81, v0
	v_sub_f32_e32 v68, v77, v0
	v_exp_f32_e32 v155, v72
	v_sub_f32_e32 v72, v82, v0
	v_exp_f32_e32 v71, v68
	v_sub_f32_e32 v68, v78, v0
	v_sub_f32_e32 v69, v79, v0
	v_exp_f32_e32 v78, v72
	v_sub_f32_e32 v72, v83, v0
	v_sub_f32_e32 v207, v154, v206
	v_exp_f32_e32 v154, v69
	v_sub_f32_e32 v69, v80, v0
	v_exp_f32_e32 v80, v72
	v_sub_f32_e32 v72, v84, v0
	v_exp_f32_e32 v79, v72
	v_sub_f32_e32 v72, v85, v0
	v_exp_f32_e32 v81, v72
	v_sub_f32_e32 v72, v86, v0
	v_exp_f32_e32 v82, v72
	v_sub_f32_e32 v72, v87, v0
	v_exp_f32_e32 v84, v72
	v_sub_f32_e32 v72, v88, v0
	v_exp_f32_e32 v83, v72
	v_sub_f32_e32 v72, v89, v0
	v_exp_f32_e32 v85, v72
	v_sub_f32_e32 v72, v90, v0
	v_exp_f32_e32 v86, v72
	v_sub_f32_e32 v72, v91, v0
	v_exp_f32_e32 v88, v72
	v_sub_f32_e32 v72, v92, v0
	v_exp_f32_e32 v161, v66
	v_sub_f32_e32 v66, v73, v0
	v_sub_f32_e32 v67, v75, v0
	v_exp_f32_e32 v87, v72
	v_sub_f32_e32 v72, v93, v0
	v_exp_f32_e32 v163, v66
	v_sub_f32_e32 v66, v74, v0
	v_exp_f32_e32 v70, v67
	v_sub_f32_e32 v67, v76, v0
	v_exp_f32_e32 v89, v72
	v_sub_f32_e32 v72, v94, v0
	v_exp_f32_e32 v66, v66
	v_exp_f32_e32 v67, v67
	v_exp_f32_e32 v74, v72
	v_sub_f32_e32 v72, v95, v0
	v_exp_f32_e32 v68, v68
	v_exp_f32_e32 v69, v69
	v_exp_f32_e32 v76, v72
	v_sub_f32_e32 v72, v96, v0
	v_exp_f32_e32 v75, v72
	v_add_f32_e32 v72, 0, v156
	v_add_f32_e32 v73, 0, v157
	v_add_f32_e32 v90, 0, v158
	v_add_f32_e32 v91, 0, v159
	v_add_f32_e32 v72, v160, v72
	v_add_f32_e32 v73, v161, v73
	v_add_f32_e32 v90, v162, v90
	v_add_f32_e32 v91, v163, v91
	v_sub_f32_e32 v0, v97, v0
	v_add_f32_e32 v72, v66, v72
	v_add_f32_e32 v73, v67, v73
	v_add_f32_e32 v90, v70, v90
	v_add_f32_e32 v91, v71, v91
	v_exp_f32_e32 v77, v0
	v_add_f32_e32 v72, v68, v72
	v_add_f32_e32 v73, v69, v73
	v_add_f32_e32 v90, v154, v90
	v_add_f32_e32 v91, v155, v91
	v_add_f32_e32 v72, v78, v72
	v_add_f32_e32 v73, v79, v73
	v_add_f32_e32 v90, v80, v90
	v_add_f32_e32 v91, v81, v91
	v_cvt_pk_bf16_f32 v66, v66, v70
	v_cvt_pk_bf16_f32 v67, v67, v71
	v_cvt_pk_bf16_f32 v70, v156, v158
	v_cvt_pk_bf16_f32 v71, v157, v159
	ds_read2st64_b64 v[92:95], v182 offset0:16 offset1:32
	ds_read2st64_b64 v[156:159], v183 offset0:16 offset1:32
	v_add_f32_e32 v72, v82, v72
	v_add_f32_e32 v73, v83, v73
	v_add_f32_e32 v90, v84, v90
	v_add_f32_e32 v91, v85, v91
	v_add_f32_e32 v72, v86, v72
	v_add_f32_e32 v73, v87, v73
	v_add_f32_e32 v90, v88, v90
	v_add_f32_e32 v91, v89, v91
	v_add_f32_e32 v72, v74, v72
	v_add_f32_e32 v73, v75, v73
	v_add_f32_e32 v90, v76, v90
	v_add_f32_e32 v91, v77, v91
	v_exp_f32_e32 v0, v207
	v_add_f32_e32 v72, v72, v90
	v_add_f32_e32 v73, v73, v91
	v_cvt_pk_bf16_f32 v68, v68, v154
	v_add_f32_e32 v90, v72, v73
	v_cvt_pk_bf16_f32 v72, v160, v162
	v_cvt_pk_bf16_f32 v73, v161, v163
	s_waitcnt lgkmcnt(1)
	v_mov_b32_e32 v160, v92
	v_mov_b32_e32 v161, v93
	s_waitcnt lgkmcnt(0)
	v_mov_b32_e32 v162, v156
	v_mov_b32_e32 v163, v157
	v_cmp_neq_f32_e32 vcc, 1.0, v0
	s_cmp_eq_u64 vcc, 0
	s_cbranch_scc1 .Lda_skip1
	v_mul_f32_e32 v48, v0, v48
	v_mul_f32_e32 v49, v0, v49
	v_mul_f32_e32 v46, v0, v46
	v_mul_f32_e32 v47, v0, v47
	v_mul_f32_e32 v44, v0, v44
	v_mul_f32_e32 v45, v0, v45
	v_mul_f32_e32 v42, v0, v42
	v_mul_f32_e32 v43, v0, v43
	v_mul_f32_e32 v40, v0, v40
	v_mul_f32_e32 v41, v0, v41
	v_mul_f32_e32 v38, v0, v38
	v_mul_f32_e32 v39, v0, v39
	v_mul_f32_e32 v36, v0, v36
	v_mul_f32_e32 v37, v0, v37
	v_mul_f32_e32 v34, v0, v34
	v_mul_f32_e32 v35, v0, v35
.Lda_skip1:
	v_mov_b32_e32 v156, v94
	v_mov_b32_e32 v157, v95
	v_mfma_f32_32x32x16_bf16 v[34:49], v[160:163], v[70:73], v[34:49]
	ds_read_b64 v[160:161], v184 offset:8192
	ds_read_b64 v[162:163], v185 offset:8192
	ds_read_b64 v[92:93], v186 offset:8192
	ds_read_b64 v[94:95], v187 offset:8192
	s_cbranch_scc1 .Lda_skip2
	v_mul_f32_e64 v64, v64, v0
	v_mul_f32_e64 v65, v65, v0
	v_mul_f32_e32 v62, v0, v62
	v_mul_f32_e32 v63, v0, v63
	v_mul_f32_e32 v60, v0, v60
	v_mul_f32_e32 v61, v0, v61
	v_mul_f32_e32 v58, v0, v58
	v_mul_f32_e32 v59, v0, v59
	v_mul_f32_e32 v56, v0, v56
	v_mul_f32_e32 v57, v0, v57
	v_mul_f32_e32 v54, v0, v54
	v_mul_f32_e32 v55, v0, v55
	v_mul_f32_e32 v52, v0, v52
	v_mul_f32_e32 v53, v0, v53
	v_mul_f32_e32 v50, v0, v50
	v_mul_f32_e32 v51, v0, v51
	v_mul_f32_e32 v32, v0, v32
	v_mul_f32_e32 v33, v0, v33
	v_mul_f32_e32 v30, v0, v30
	v_mul_f32_e32 v31, v0, v31
	v_mul_f32_e32 v28, v0, v28
	v_mul_f32_e32 v29, v0, v29
	v_mul_f32_e32 v26, v0, v26
	v_mul_f32_e32 v27, v0, v27
	v_mul_f32_e32 v24, v0, v24
	v_mul_f32_e32 v25, v0, v25
	v_mul_f32_e32 v22, v0, v22
	v_mul_f32_e32 v23, v0, v23
	v_mul_f32_e32 v20, v0, v20
	v_mul_f32_e32 v21, v0, v21
	v_mul_f32_e32 v18, v0, v18
	v_mul_f32_e32 v19, v0, v19
	v_mul_f32_e32 v16, v0, v16
	v_mul_f32_e32 v17, v0, v17
	v_mul_f32_e32 v14, v0, v14
	v_mul_f32_e32 v15, v0, v15
	v_mul_f32_e32 v12, v0, v12
	v_mul_f32_e32 v13, v0, v13
	v_mul_f32_e32 v10, v0, v10
	v_mul_f32_e32 v11, v0, v11
	v_mul_f32_e32 v8, v0, v8
	v_mul_f32_e32 v9, v0, v9
	v_mul_f32_e32 v6, v0, v6
	v_mul_f32_e32 v7, v0, v7
	v_mul_f32_e32 v4, v0, v4
	v_mul_f32_e32 v5, v0, v5
	v_mul_f32_e32 v2, v0, v2
	v_mul_f32_e32 v3, v0, v3
.Lda_skip2:
	s_waitcnt lgkmcnt(2)
	v_mfma_f32_32x32x16_bf16 v[50:65], v[160:163], v[70:73], v[50:65]
	v_cvt_pk_bf16_f32 v69, v69, v155
	v_fmac_f32_e32 v90, v178, v0
	v_mov_b32_e32 v178, v90
	v_mfma_f32_32x32x16_bf16 v[18:33], v[156:159], v[70:73], v[18:33]
	s_waitcnt lgkmcnt(0)
	v_mfma_f32_32x32x16_bf16 v[2:17], v[92:95], v[70:73], v[2:17]
	ds_read2st64_b64 v[70:73], v188 offset0:16 offset1:32
	ds_read2st64_b64 v[92:95], v189 offset0:16 offset1:32
	s_waitcnt lgkmcnt(1)
	v_mov_b32_e32 v154, v70
	v_mov_b32_e32 v155, v71
	s_waitcnt lgkmcnt(0)
	v_mov_b32_e32 v156, v92
	v_mov_b32_e32 v157, v93
	v_mov_b32_e32 v92, v72
	v_mov_b32_e32 v93, v73
	v_mfma_f32_32x32x16_bf16 v[34:49], v[154:157], v[66:69], v[34:49]
	ds_read_b64 v[154:155], v190 offset:8192
	ds_read_b64 v[156:157], v191 offset:8192
	ds_read_b64 v[70:71], v192 offset:8192
	ds_read_b64 v[72:73], v193 offset:8192
	s_waitcnt lgkmcnt(0)
	v_mfma_f32_32x32x16_bf16 v[2:17], v[70:73], v[66:69], v[2:17]
	v_cvt_pk_bf16_f32 v70, v78, v80
	v_cvt_pk_bf16_f32 v71, v79, v81
	v_cvt_pk_bf16_f32 v72, v82, v84
	v_cvt_pk_bf16_f32 v73, v83, v85
	ds_read2st64_b64 v[78:81], v194 offset0:16 offset1:32
	ds_read2st64_b64 v[82:85], v195 offset0:16 offset1:32
	v_mfma_f32_32x32x16_bf16 v[50:65], v[154:157], v[66:69], v[50:65]
	v_mov_b32_e32 v154, v206
	v_mfma_f32_32x32x16_bf16 v[18:33], v[92:95], v[66:69], v[18:33]
	v_cvt_pk_bf16_f32 v66, v86, v88
	v_cvt_pk_bf16_f32 v67, v87, v89
	s_waitcnt lgkmcnt(1)
	v_mov_b32_e32 v86, v78
	v_mov_b32_e32 v87, v79
	s_waitcnt lgkmcnt(0)
	v_mov_b32_e32 v88, v82
	v_mov_b32_e32 v89, v83
	v_mov_b32_e32 v82, v80
	v_mov_b32_e32 v83, v81
	v_mfma_f32_32x32x16_bf16 v[34:49], v[86:89], v[70:73], v[34:49]
	ds_read_b64 v[86:87], v196 offset:8192
	ds_read_b64 v[88:89], v197 offset:8192
	ds_read_b64 v[78:79], v198 offset:8192
	ds_read_b64 v[80:81], v199 offset:8192
	v_cvt_pk_bf16_f32 v68, v74, v76
	v_cvt_pk_bf16_f32 v69, v75, v77
	s_waitcnt lgkmcnt(2)
	v_mfma_f32_32x32x16_bf16 v[50:65], v[86:89], v[70:73], v[50:65]
	v_mfma_f32_32x32x16_bf16 v[18:33], v[82:85], v[70:73], v[18:33]
	s_waitcnt lgkmcnt(0)
	v_mfma_f32_32x32x16_bf16 v[2:17], v[78:81], v[70:73], v[2:17]
	ds_read2st64_b64 v[70:73], v200 offset0:16 offset1:32
	ds_read2st64_b64 v[74:77], v201 offset0:16 offset1:32
	s_waitcnt lgkmcnt(1)
	v_mov_b32_e32 v78, v70
	v_mov_b32_e32 v79, v71
	s_waitcnt lgkmcnt(0)
	v_mov_b32_e32 v80, v74
	v_mov_b32_e32 v81, v75
	v_mov_b32_e32 v74, v72
	v_mov_b32_e32 v75, v73
	v_mfma_f32_32x32x16_bf16 v[34:49], v[78:81], v[66:69], v[34:49]
	ds_read_b64 v[78:79], v202 offset:8192
	ds_read_b64 v[80:81], v203 offset:8192
	ds_read_b64 v[70:71], v204 offset:8192
	ds_read_b64 v[72:73], v205 offset:8192
	s_waitcnt lgkmcnt(2)
	v_mfma_f32_32x32x16_bf16 v[50:65], v[78:81], v[66:69], v[50:65]
	v_mfma_f32_32x32x16_bf16 v[18:33], v[74:77], v[66:69], v[18:33]
	s_waitcnt lgkmcnt(0)
	v_mfma_f32_32x32x16_bf16 v[2:17], v[70:73], v[66:69], v[2:17]

.LBB0_116:
	s_or_b64 exec, exec, s[14:15]
	s_add_i32 s14, s30, 0xfc0
	v_cmp_le_i32_e32 vcc, s14, v153
	s_and_saveexec_b64 s[22:23], vcc
	s_cbranch_execz .LBB0_113
	v_add_u32_e32 v66, v174, v173
	v_add_u32_e32 v208, v174, v175
	v_add_u32_e32 v212, v174, v176
	v_add_u32_e32 v216, v174, v177
	ds_read_b128 v[66:69], v66
	ds_read_b128 v[208:211], v208
	ds_read_b128 v[212:215], v212
	ds_read_b128 v[216:219], v216
	v_add_u32_e32 v82, v179, v173
	v_add_u32_e32 v220, v179, v175
	v_add_u32_e32 v156, v179, v176
	v_add_u32_e32 v224, v179, v177
	ds_read_b128 v[82:85], v82
	ds_read_b128 v[220:223], v220
	ds_read_b128 v[156:159], v156
	ds_read_b128 v[224:227], v224
	s_addk_i32 s30, 0xfff
	v_cmp_gt_i32_e32 vcc, s30, v172
	s_waitcnt lgkmcnt(7)
	v_mfma_f32_32x32x16_bf16 v[66:81], v[66:69], v[98:101], 0
	s_waitcnt lgkmcnt(6)
	v_mfma_f32_32x32x16_bf16 v[66:81], v[208:211], v[102:105], v[66:81]
	s_waitcnt lgkmcnt(5)
	v_mfma_f32_32x32x16_bf16 v[66:81], v[212:215], v[106:109], v[66:81]
	s_waitcnt lgkmcnt(4)
	v_mfma_f32_32x32x16_bf16 v[66:81], v[216:219], v[110:113], v[66:81]
	s_waitcnt lgkmcnt(3)
	v_mfma_f32_32x32x16_bf16 v[82:97], v[82:85], v[98:101], 0
	s_waitcnt lgkmcnt(2)
	v_mfma_f32_32x32x16_bf16 v[82:97], v[220:223], v[102:105], v[82:97]
	s_waitcnt lgkmcnt(1)
	v_mfma_f32_32x32x16_bf16 v[82:97], v[156:159], v[106:109], v[82:97]
	s_waitcnt lgkmcnt(0)
	v_mfma_f32_32x32x16_bf16 v[82:97], v[224:227], v[110:113], v[82:97]
	v_mov_b32_e32 v226, 0x8000
	v_mfma_f32_32x32x16_bf16 v[66:81], v[126:129], v[130:133], v[66:81]
	v_mfma_f32_32x32x16_bf16 v[82:97], v[122:125], v[130:133], v[82:97]
	s_and_saveexec_b64 s[14:15], vcc
	s_cbranch_execz .LBB0_112
	v_add_u32_e32 v0, s28, v181
	v_add_u32_e32 v155, 0xfc0, v0
	v_cmp_lt_i32_e32 vcc, v168, v155
	s_nop 5
	v_cndmask_b32_e32 v156, v66, v245, vcc
	v_cmp_gt_i32_e32 vcc, v168, v155
	v_add_u32_e32 v155, 0xfc2, v0
	s_nop 0
	v_cndmask_b32_e32 v66, v156, v66, vcc
	v_cndmask_b32_e32 v67, v245, v67, vcc
	v_cmp_ge_i32_e32 vcc, v168, v155
	v_add_u32_e32 v155, 0xfc3, v0
	s_nop 0
	v_cndmask_b32_e32 v68, v245, v68, vcc
	v_cmp_ge_i32_e32 vcc, v168, v155
	v_add_u32_e32 v155, 0xfc8, v0
	s_nop 0
	v_cndmask_b32_e32 v69, v245, v69, vcc
	v_cmp_ge_i32_e32 vcc, v168, v155
	v_add_u32_e32 v155, 0xfc9, v0
	s_nop 0
	v_cndmask_b32_e32 v70, v245, v70, vcc
	v_cmp_ge_i32_e32 vcc, v168, v155
	v_add_u32_e32 v155, 0xfca, v0
	s_nop 0
	v_cndmask_b32_e32 v71, v245, v71, vcc
	v_cmp_ge_i32_e32 vcc, v168, v155
	v_add_u32_e32 v155, 0xfcb, v0
	s_nop 0
	v_cndmask_b32_e32 v72, v245, v72, vcc
	v_cmp_ge_i32_e32 vcc, v168, v155
	v_add_u32_e32 v155, 0xfd0, v0
	s_nop 0
	v_cndmask_b32_e32 v73, v245, v73, vcc
	v_cmp_ge_i32_e32 vcc, v168, v155
	v_add_u32_e32 v155, 0xfd1, v0
	s_nop 0
	v_cndmask_b32_e32 v74, v245, v74, vcc
	v_cmp_ge_i32_e32 vcc, v168, v155
	v_add_u32_e32 v155, 0xfd2, v0
	s_nop 0
	v_cndmask_b32_e32 v75, v245, v75, vcc
	v_cmp_ge_i32_e32 vcc, v168, v155
	v_add_u32_e32 v155, 0xfd3, v0
	s_nop 0
	v_cndmask_b32_e32 v76, v245, v76, vcc
	v_cmp_ge_i32_e32 vcc, v168, v155
	v_add_u32_e32 v155, 0xfd8, v0
	s_nop 0
	v_cndmask_b32_e32 v77, v245, v77, vcc
	v_cmp_ge_i32_e32 vcc, v168, v155
	v_add_u32_e32 v155, 0xfd9, v0
	s_nop 0
	v_cndmask_b32_e32 v78, v245, v78, vcc
	v_cmp_ge_i32_e32 vcc, v168, v155
	v_add_u32_e32 v155, 0xfda, v0
	s_nop 0
	v_cndmask_b32_e32 v79, v245, v79, vcc
	v_cmp_ge_i32_e32 vcc, v168, v155
	v_add_u32_e32 v155, 0xfdb, v0
	s_nop 0
	v_cndmask_b32_e32 v80, v245, v80, vcc
	v_cmp_ge_i32_e32 vcc, v168, v155
	v_add_u32_e32 v155, 0xfe0, v0
	s_nop 0
	v_cndmask_b32_e32 v81, v245, v81, vcc
	v_cmp_ge_i32_e32 vcc, v168, v155
	v_add_u32_e32 v155, 0xfe1, v0
	s_nop 0
	v_cndmask_b32_e32 v82, v245, v82, vcc
	v_cmp_ge_i32_e32 vcc, v168, v155
	v_add_u32_e32 v155, 0xfe2, v0
	s_nop 0
	v_cndmask_b32_e32 v83, v245, v83, vcc
	v_cmp_ge_i32_e32 vcc, v168, v155
	v_add_u32_e32 v155, 0xfe3, v0
	s_nop 0
	v_cndmask_b32_e32 v84, v245, v84, vcc
	v_cmp_ge_i32_e32 vcc, v168, v155
	v_add_u32_e32 v155, 0xfe8, v0
	s_nop 0
	v_cndmask_b32_e32 v85, v245, v85, vcc
	v_cmp_ge_i32_e32 vcc, v168, v155
	v_add_u32_e32 v155, 0xfe9, v0
	s_nop 0
	v_cndmask_b32_e32 v86, v245, v86, vcc
	v_cmp_ge_i32_e32 vcc, v168, v155
	v_add_u32_e32 v155, 0xfea, v0
	s_nop 0
	v_cndmask_b32_e32 v87, v245, v87, vcc
	v_cmp_ge_i32_e32 vcc, v168, v155
	v_add_u32_e32 v155, 0xfeb, v0
	s_nop 0
	v_cndmask_b32_e32 v88, v245, v88, vcc
	v_cmp_ge_i32_e32 vcc, v168, v155
	v_add_u32_e32 v155, 0xff0, v0
	s_nop 0
	v_cndmask_b32_e32 v89, v245, v89, vcc
	v_cmp_ge_i32_e32 vcc, v168, v155
	v_add_u32_e32 v155, 0xff1, v0
	s_nop 0
	v_cndmask_b32_e32 v90, v245, v90, vcc
	v_cmp_ge_i32_e32 vcc, v168, v155
	v_add_u32_e32 v155, 0xff2, v0
	s_nop 0
	v_cndmask_b32_e32 v91, v245, v91, vcc
	v_cmp_ge_i32_e32 vcc, v168, v155
	v_add_u32_e32 v155, 0xff3, v0
	s_nop 0
	v_cndmask_b32_e32 v92, v245, v92, vcc
	v_cmp_ge_i32_e32 vcc, v168, v155
	v_add_u32_e32 v155, 0xff8, v0
	s_nop 0
	v_cndmask_b32_e32 v93, v245, v93, vcc
	v_cmp_ge_i32_e32 vcc, v168, v155
	v_add_u32_e32 v155, 0xff9, v0
	s_nop 0
	v_cndmask_b32_e32 v94, v245, v94, vcc
	v_cmp_ge_i32_e32 vcc, v168, v155
	v_add_u32_e32 v155, 0xffa, v0
	v_add_u32_e32 v0, 0xffb, v0
	v_cndmask_b32_e32 v95, v245, v95, vcc
	v_cmp_ge_i32_e32 vcc, v168, v155
	s_nop 1
	v_cndmask_b32_e32 v96, v245, v96, vcc
	v_cmp_ge_i32_e32 vcc, v168, v0
	s_nop 1
	v_cndmask_b32_e32 v97, v245, v97, vcc
	s_branch .LBB0_112
